# v22 + scan pass 1 skips the last super-chunk's units (their transfer state is never read by pass 2)
# speedup vs baseline: 1.0028x; 1.0003x over previous
; #define GAS __attribute__((address_space(1)))
; __device__ __forceinline__ float sigmoidf_(float x) { return __builtin_amdgcn_rcpf(1.0f + __expf(-x)); }
; template <int pass> __device__ __forceinline__ void scan_phase(LAS unsigned char* lds, const bf16* P  , bf16* OB, float* scr, const float* lb0, const float* lb1, int jl, const float* onorm, int u_lo, int u_hi) {
;     ...
;     for (int u = u_lo + blockIdx.x; u < u_hi; u += gridDim.x) {
;         const int sc = u & 7, h = (u >> 3) & 7, b = u >> 6;
;         const size_t tok0 = (size_t)b * SEQ + sc * 512;
;         f32x16 S[2];
; #pragma unroll
;         for (int i = 0; i < 16; ++i) { S[0][i] = 0.f; S[1][i] = 0.f; }
;         if (pass == 2) {
;             for (int p = 0; p < sc; ++p) { const GAS float* Tp = (const GAS float*)Tg + (size_t)(u - sc + p) * 16384 + wave * 2048 + (tid & 63); const GAS float* Dp = (const GAS float*)Dg + (size_t)(u - sc + p) * 4096 + kh * 2048 + (tid & 63);
;                 asm volatile("" : "+v"(Tp), "+v"(Dp));
; #pragma unroll
;                 for (int j2 = 0; j2 < 2; ++j2)
; #pragma unroll
;                     for (int i = 0; i < 16; ++i) S[j2][i] = Dp[(j2 * 16 + i) * 64] * S[j2][i] + Tp[(j2 * 16 + i) * 64]; }
;         }
;         float gsum = 1.f;
;         float lb = 0.f; if (jl) lb = sigmoidf_(((const GAS float*)lb1)[h * 128 + (tid & 127)] - ((const GAS float*)lb0)[h * 128 + (tid & 127)]);
.LBB0_105:
	s_and_b32 s15, s42, 7
	s_cmp_eq_u32 s15, 7
	s_cbranch_scc1 .LBB0_104
	v_readlane_b32 s26, v250, 34
	s_lshl_b32 s15, s42, 4
	v_readlane_b32 s27, v250, 35
	s_and_b32 s15, s15, 0x380
	v_mov_b32_e32 v114, 0
	s_andn2_b64 vcc, exec, s[26:27]
	v_mov_b32_e32 v152, 0
	s_cbranch_vccnz .LBB0_107
	v_or_b32_e32 v0, s15, v102
	v_readlane_b32 s44, v251, 4
	v_lshlrev_b32_e32 v0, 2, v0
	v_readlane_b32 s54, v251, 14
	v_readlane_b32 s55, v251, 15
	global_load_dword v2, v0, s[88:89]
	v_readlane_b32 s45, v251, 5
	v_readlane_b32 s46, v251, 6
	v_readlane_b32 s47, v251, 7
	v_readlane_b32 s48, v251, 8
	global_load_dword v0, v0, s[54:55]
	v_readlane_b32 s49, v251, 9
	v_readlane_b32 s50, v251, 10
	v_readlane_b32 s51, v251, 11
	v_readlane_b32 s52, v251, 12
	v_readlane_b32 s53, v251, 13
	v_readlane_b32 s56, v251, 16
	v_readlane_b32 s57, v251, 17
	v_readlane_b32 s58, v251, 18
	v_readlane_b32 s59, v251, 19
	s_waitcnt vmcnt(0)
	v_sub_f32_e32 v0, v2, v0
	v_mul_f32_e32 v0, 0xbfb8aa3b, v0
	v_exp_f32_e32 v0, v0
	s_nop 0
	v_add_f32_e32 v0, 1.0, v0
	v_rcp_f32_e32 v152, v0
